# xo GEMM residual epilogue hand-written: all 16 residual loads in flight, counted vmcnt(15) per quad, row statistics finished at the end
# speedup vs baseline: 1.0093x; 1.0024x over previous
.LBB0_110:
	v_readlane_b32 s4, v250, 25
	v_mbcnt_lo_u32_b32 v138, -1, 0
	v_mbcnt_hi_u32_b32 v138, -1, v138
	s_nop 1
	s_lshr_b32 s5, s4, 8
	s_bfe_u32 s4, s4, 0x20006
	v_and_b32_e32 v139, 15, v138
	v_lshrrev_b32_e32 v148, 4, v138
	s_lshl_b32 s70, s29, 8
	s_lshl_b32 s5, s5, 6
	s_add_u32 s5, s5, s70
	v_add_u32_e32 v139, s5, v139
	v_lshlrev_b32_e32 v149, 6, v139
	v_lshlrev_b32_e32 v150, 11, v139
	v_lshl_add_u32 v150, v148, 4, v150
	s_lshl_b32 s71, s4, 6
	v_add_u32_e32 v150, s71, v150
	v_mov_b32_e32 v151, v150
	s_lshl_b32 s70, s28, 9
	s_add_u32 s74, s30, s70
	s_addc_u32 s75, s31, 0
	s_lshl_b32 s57, s28, 2
	s_lshl_b32 s56, s28, 4
	s_lshl_b32 s76, s4, 2
	s_add_u32 s56, s56, s76
	v_readlane_b32 s28, v250, 26
	v_readlane_b32 s29, v250, 27
	global_load_dwordx4 v[184:187], v150, s[74:75]
	global_load_dwordx4 v[188:191], v150, s[74:75] offset:256
	v_add_u32_e32 v150, 0x8000, v150
	global_load_dwordx4 v[192:195], v150, s[74:75]
	global_load_dwordx4 v[196:199], v150, s[74:75] offset:256
	v_add_u32_e32 v150, 0x8000, v150
	global_load_dwordx4 v[200:203], v150, s[74:75]
	global_load_dwordx4 v[204:207], v150, s[74:75] offset:256
	v_add_u32_e32 v150, 0x8000, v150
	global_load_dwordx4 v[208:211], v150, s[74:75]
	global_load_dwordx4 v[212:215], v150, s[74:75] offset:256
	v_add_u32_e32 v150, 0x28000, v150
	global_load_dwordx4 v[216:219], v150, s[74:75]
	global_load_dwordx4 v[220:223], v150, s[74:75] offset:256
	v_add_u32_e32 v150, 0x8000, v150
	global_load_dwordx4 v[224:227], v150, s[74:75]
	global_load_dwordx4 v[228:231], v150, s[74:75] offset:256
	v_add_u32_e32 v150, 0x8000, v150
	global_load_dwordx4 v[232:235], v150, s[74:75]
	global_load_dwordx4 v[236:239], v150, s[74:75] offset:256
	v_add_u32_e32 v150, 0x8000, v150
	global_load_dwordx4 v[240:243], v150, s[74:75]
	global_load_dwordx4 v[244:247], v150, s[74:75] offset:256
	s_waitcnt vmcnt(15)
	v_lshlrev_b32_e32 v182, 16, v184
	v_and_b32_e32 v183, 0xffff0000, v184
	v_pk_add_f32 v[126:127], v[126:127], v[182:183]
	v_lshlrev_b32_e32 v248, 16, v185
	v_and_b32_e32 v249, 0xffff0000, v185
	v_pk_add_f32 v[128:129], v[128:129], v[248:249]
	v_lshlrev_b32_e32 v138, 16, v186
	v_and_b32_e32 v139, 0xffff0000, v186
	v_pk_add_f32 v[122:123], v[122:123], v[138:139]
	v_lshlrev_b32_e32 v182, 16, v187
	v_and_b32_e32 v183, 0xffff0000, v187
	v_pk_add_f32 v[124:125], v[124:125], v[182:183]
	v_cvt_pk_bf16_f32 v126, v126, v127
	v_cvt_pk_bf16_f32 v127, v128, v129
	v_cvt_pk_bf16_f32 v128, v122, v123
	v_cvt_pk_bf16_f32 v129, v124, v125
	global_store_dwordx4 v151, v[126:129], s[74:75]
	v_lshlrev_b32_e32 v184, 16, v126
	v_lshlrev_b32_e32 v185, 16, v127
	v_lshlrev_b32_e32 v186, 16, v128
	v_lshlrev_b32_e32 v187, 16, v129
	v_and_b32_e32 v122, 0xffff0000, v126
	v_and_b32_e32 v123, 0xffff0000, v127
	v_and_b32_e32 v124, 0xffff0000, v128
	v_and_b32_e32 v125, 0xffff0000, v129
	v_mul_f32_e32 v122, v122, v122
	v_mul_f32_e32 v123, v123, v123
	v_mul_f32_e32 v124, v124, v124
	v_mul_f32_e32 v125, v125, v125
	v_fmac_f32_e32 v122, v184, v184
	v_fmac_f32_e32 v123, v185, v185
	v_fmac_f32_e32 v124, v186, v186
	v_fmac_f32_e32 v125, v187, v187
	v_add_f32_e32 v122, v122, v123
	v_add_f32_e32 v122, v122, v124
	v_add_f32_e32 v122, v122, v125
	s_waitcnt vmcnt(15)
	v_lshlrev_b32_e32 v182, 16, v188
	v_and_b32_e32 v183, 0xffff0000, v188
	v_pk_add_f32 v[118:119], v[118:119], v[182:183]
	v_lshlrev_b32_e32 v248, 16, v189
	v_and_b32_e32 v249, 0xffff0000, v189
	v_pk_add_f32 v[120:121], v[120:121], v[248:249]
	v_lshlrev_b32_e32 v138, 16, v190
	v_and_b32_e32 v139, 0xffff0000, v190
	v_pk_add_f32 v[114:115], v[114:115], v[138:139]
	v_lshlrev_b32_e32 v182, 16, v191
	v_and_b32_e32 v183, 0xffff0000, v191
	v_pk_add_f32 v[116:117], v[116:117], v[182:183]
	v_cvt_pk_bf16_f32 v118, v118, v119
	v_cvt_pk_bf16_f32 v119, v120, v121
	v_cvt_pk_bf16_f32 v120, v114, v115
	v_cvt_pk_bf16_f32 v121, v116, v117
	global_store_dwordx4 v151, v[118:121], s[74:75] offset:256
	v_lshlrev_b32_e32 v188, 16, v118
	v_lshlrev_b32_e32 v189, 16, v119
	v_lshlrev_b32_e32 v190, 16, v120
	v_lshlrev_b32_e32 v191, 16, v121
	v_and_b32_e32 v114, 0xffff0000, v118
	v_and_b32_e32 v115, 0xffff0000, v119
	v_and_b32_e32 v116, 0xffff0000, v120
	v_and_b32_e32 v117, 0xffff0000, v121
	v_mul_f32_e32 v114, v114, v114
	v_mul_f32_e32 v115, v115, v115
	v_mul_f32_e32 v116, v116, v116
	v_mul_f32_e32 v117, v117, v117
	v_fmac_f32_e32 v114, v188, v188
	v_fmac_f32_e32 v115, v189, v189
	v_fmac_f32_e32 v116, v190, v190
	v_fmac_f32_e32 v117, v191, v191
	v_add_f32_e32 v114, v114, v115
	v_add_f32_e32 v114, v114, v116
	v_add_f32_e32 v114, v114, v117
	v_add_f32_e32 v122, v122, v114
	v_add_u32_e32 v151, 0x8000, v151
	s_waitcnt vmcnt(15)
	v_lshlrev_b32_e32 v182, 16, v192
	v_and_b32_e32 v183, 0xffff0000, v192
	v_pk_add_f32 v[110:111], v[110:111], v[182:183]
	v_lshlrev_b32_e32 v248, 16, v193
	v_and_b32_e32 v249, 0xffff0000, v193
	v_pk_add_f32 v[112:113], v[112:113], v[248:249]
	v_lshlrev_b32_e32 v138, 16, v194
	v_and_b32_e32 v139, 0xffff0000, v194
	v_pk_add_f32 v[106:107], v[106:107], v[138:139]
	v_lshlrev_b32_e32 v182, 16, v195
	v_and_b32_e32 v183, 0xffff0000, v195
	v_pk_add_f32 v[108:109], v[108:109], v[182:183]
	v_cvt_pk_bf16_f32 v110, v110, v111
	v_cvt_pk_bf16_f32 v111, v112, v113
	v_cvt_pk_bf16_f32 v112, v106, v107
	v_cvt_pk_bf16_f32 v113, v108, v109
	global_store_dwordx4 v151, v[110:113], s[74:75]
	v_lshlrev_b32_e32 v192, 16, v110
	v_lshlrev_b32_e32 v193, 16, v111
	v_lshlrev_b32_e32 v194, 16, v112
	v_lshlrev_b32_e32 v195, 16, v113
	v_and_b32_e32 v106, 0xffff0000, v110
	v_and_b32_e32 v107, 0xffff0000, v111
	v_and_b32_e32 v108, 0xffff0000, v112
	v_and_b32_e32 v109, 0xffff0000, v113
	v_mul_f32_e32 v106, v106, v106
	v_mul_f32_e32 v107, v107, v107
	v_mul_f32_e32 v108, v108, v108
	v_mul_f32_e32 v109, v109, v109
	v_fmac_f32_e32 v106, v192, v192
	v_fmac_f32_e32 v107, v193, v193
	v_fmac_f32_e32 v108, v194, v194
	v_fmac_f32_e32 v109, v195, v195
	v_add_f32_e32 v106, v106, v107
	v_add_f32_e32 v106, v106, v108
	v_add_f32_e32 v106, v106, v109
	s_waitcnt vmcnt(15)
	v_lshlrev_b32_e32 v182, 16, v196
	v_and_b32_e32 v183, 0xffff0000, v196
	v_pk_add_f32 v[102:103], v[102:103], v[182:183]
	v_lshlrev_b32_e32 v248, 16, v197
	v_and_b32_e32 v249, 0xffff0000, v197
	v_pk_add_f32 v[104:105], v[104:105], v[248:249]
	v_lshlrev_b32_e32 v138, 16, v198
	v_and_b32_e32 v139, 0xffff0000, v198
	v_pk_add_f32 v[98:99], v[98:99], v[138:139]
	v_lshlrev_b32_e32 v182, 16, v199
	v_and_b32_e32 v183, 0xffff0000, v199
	v_pk_add_f32 v[100:101], v[100:101], v[182:183]
	v_cvt_pk_bf16_f32 v102, v102, v103
	v_cvt_pk_bf16_f32 v103, v104, v105
	v_cvt_pk_bf16_f32 v104, v98, v99
	v_cvt_pk_bf16_f32 v105, v100, v101
	global_store_dwordx4 v151, v[102:105], s[74:75] offset:256
	v_lshlrev_b32_e32 v196, 16, v102
	v_lshlrev_b32_e32 v197, 16, v103
	v_lshlrev_b32_e32 v198, 16, v104
	v_lshlrev_b32_e32 v199, 16, v105
	v_and_b32_e32 v98, 0xffff0000, v102
	v_and_b32_e32 v99, 0xffff0000, v103
	v_and_b32_e32 v100, 0xffff0000, v104
	v_and_b32_e32 v101, 0xffff0000, v105
	v_mul_f32_e32 v98, v98, v98
	v_mul_f32_e32 v99, v99, v99
	v_mul_f32_e32 v100, v100, v100
	v_mul_f32_e32 v101, v101, v101
	v_fmac_f32_e32 v98, v196, v196
	v_fmac_f32_e32 v99, v197, v197
	v_fmac_f32_e32 v100, v198, v198
	v_fmac_f32_e32 v101, v199, v199
	v_add_f32_e32 v98, v98, v99
	v_add_f32_e32 v98, v98, v100
	v_add_f32_e32 v98, v98, v101
	v_add_f32_e32 v106, v106, v98
	v_add_u32_e32 v151, 0x8000, v151
	s_waitcnt vmcnt(15)
	v_lshlrev_b32_e32 v182, 16, v200
	v_and_b32_e32 v183, 0xffff0000, v200
	v_pk_add_f32 v[94:95], v[94:95], v[182:183]
	v_lshlrev_b32_e32 v248, 16, v201
	v_and_b32_e32 v249, 0xffff0000, v201
	v_pk_add_f32 v[96:97], v[96:97], v[248:249]
	v_lshlrev_b32_e32 v138, 16, v202
	v_and_b32_e32 v139, 0xffff0000, v202
	v_pk_add_f32 v[90:91], v[90:91], v[138:139]
	v_lshlrev_b32_e32 v182, 16, v203
	v_and_b32_e32 v183, 0xffff0000, v203
	v_pk_add_f32 v[92:93], v[92:93], v[182:183]
	v_cvt_pk_bf16_f32 v94, v94, v95
	v_cvt_pk_bf16_f32 v95, v96, v97
	v_cvt_pk_bf16_f32 v96, v90, v91
	v_cvt_pk_bf16_f32 v97, v92, v93
	global_store_dwordx4 v151, v[94:97], s[74:75]
	v_lshlrev_b32_e32 v200, 16, v94
	v_lshlrev_b32_e32 v201, 16, v95
	v_lshlrev_b32_e32 v202, 16, v96
	v_lshlrev_b32_e32 v203, 16, v97
	v_and_b32_e32 v90, 0xffff0000, v94
	v_and_b32_e32 v91, 0xffff0000, v95
	v_and_b32_e32 v92, 0xffff0000, v96
	v_and_b32_e32 v93, 0xffff0000, v97
	v_mul_f32_e32 v90, v90, v90
	v_mul_f32_e32 v91, v91, v91
	v_mul_f32_e32 v92, v92, v92
	v_mul_f32_e32 v93, v93, v93
	v_fmac_f32_e32 v90, v200, v200
	v_fmac_f32_e32 v91, v201, v201
	v_fmac_f32_e32 v92, v202, v202
	v_fmac_f32_e32 v93, v203, v203
	v_add_f32_e32 v90, v90, v91
	v_add_f32_e32 v90, v90, v92
	v_add_f32_e32 v90, v90, v93
	s_waitcnt vmcnt(15)
	v_lshlrev_b32_e32 v182, 16, v204
	v_and_b32_e32 v183, 0xffff0000, v204
	v_pk_add_f32 v[86:87], v[86:87], v[182:183]
	v_lshlrev_b32_e32 v248, 16, v205
	v_and_b32_e32 v249, 0xffff0000, v205
	v_pk_add_f32 v[88:89], v[88:89], v[248:249]
	v_lshlrev_b32_e32 v138, 16, v206
	v_and_b32_e32 v139, 0xffff0000, v206
	v_pk_add_f32 v[82:83], v[82:83], v[138:139]
	v_lshlrev_b32_e32 v182, 16, v207
	v_and_b32_e32 v183, 0xffff0000, v207
	v_pk_add_f32 v[84:85], v[84:85], v[182:183]
	v_cvt_pk_bf16_f32 v86, v86, v87
	v_cvt_pk_bf16_f32 v87, v88, v89
	v_cvt_pk_bf16_f32 v88, v82, v83
	v_cvt_pk_bf16_f32 v89, v84, v85
	global_store_dwordx4 v151, v[86:89], s[74:75] offset:256
	v_lshlrev_b32_e32 v204, 16, v86
	v_lshlrev_b32_e32 v205, 16, v87
	v_lshlrev_b32_e32 v206, 16, v88
	v_lshlrev_b32_e32 v207, 16, v89
	v_and_b32_e32 v82, 0xffff0000, v86
	v_and_b32_e32 v83, 0xffff0000, v87
	v_and_b32_e32 v84, 0xffff0000, v88
	v_and_b32_e32 v85, 0xffff0000, v89
	v_mul_f32_e32 v82, v82, v82
	v_mul_f32_e32 v83, v83, v83
	v_mul_f32_e32 v84, v84, v84
	v_mul_f32_e32 v85, v85, v85
	v_fmac_f32_e32 v82, v204, v204
	v_fmac_f32_e32 v83, v205, v205
	v_fmac_f32_e32 v84, v206, v206
	v_fmac_f32_e32 v85, v207, v207
	v_add_f32_e32 v82, v82, v83
	v_add_f32_e32 v82, v82, v84
	v_add_f32_e32 v82, v82, v85
	v_add_f32_e32 v90, v90, v82
	v_add_u32_e32 v151, 0x8000, v151
	s_waitcnt vmcnt(15)
	v_lshlrev_b32_e32 v182, 16, v208
	v_and_b32_e32 v183, 0xffff0000, v208
	v_pk_add_f32 v[78:79], v[78:79], v[182:183]
	v_lshlrev_b32_e32 v248, 16, v209
	v_and_b32_e32 v249, 0xffff0000, v209
	v_pk_add_f32 v[80:81], v[80:81], v[248:249]
	v_lshlrev_b32_e32 v138, 16, v210
	v_and_b32_e32 v139, 0xffff0000, v210
	v_pk_add_f32 v[74:75], v[74:75], v[138:139]
	v_lshlrev_b32_e32 v182, 16, v211
	v_and_b32_e32 v183, 0xffff0000, v211
	v_pk_add_f32 v[76:77], v[76:77], v[182:183]
	v_cvt_pk_bf16_f32 v78, v78, v79
	v_cvt_pk_bf16_f32 v79, v80, v81
	v_cvt_pk_bf16_f32 v80, v74, v75
	v_cvt_pk_bf16_f32 v81, v76, v77
	global_store_dwordx4 v151, v[78:81], s[74:75]
	v_lshlrev_b32_e32 v208, 16, v78
	v_lshlrev_b32_e32 v209, 16, v79
	v_lshlrev_b32_e32 v210, 16, v80
	v_lshlrev_b32_e32 v211, 16, v81
	v_and_b32_e32 v74, 0xffff0000, v78
	v_and_b32_e32 v75, 0xffff0000, v79
	v_and_b32_e32 v76, 0xffff0000, v80
	v_and_b32_e32 v77, 0xffff0000, v81
	v_mul_f32_e32 v74, v74, v74
	v_mul_f32_e32 v75, v75, v75
	v_mul_f32_e32 v76, v76, v76
	v_mul_f32_e32 v77, v77, v77
	v_fmac_f32_e32 v74, v208, v208
	v_fmac_f32_e32 v75, v209, v209
	v_fmac_f32_e32 v76, v210, v210
	v_fmac_f32_e32 v77, v211, v211
	v_add_f32_e32 v74, v74, v75
	v_add_f32_e32 v74, v74, v76
	v_add_f32_e32 v74, v74, v77
	s_waitcnt vmcnt(15)
	v_lshlrev_b32_e32 v182, 16, v212
	v_and_b32_e32 v183, 0xffff0000, v212
	v_pk_add_f32 v[70:71], v[70:71], v[182:183]
	v_lshlrev_b32_e32 v248, 16, v213
	v_and_b32_e32 v249, 0xffff0000, v213
	v_pk_add_f32 v[72:73], v[72:73], v[248:249]
	v_lshlrev_b32_e32 v138, 16, v214
	v_and_b32_e32 v139, 0xffff0000, v214
	v_pk_add_f32 v[66:67], v[66:67], v[138:139]
	v_lshlrev_b32_e32 v182, 16, v215
	v_and_b32_e32 v183, 0xffff0000, v215
	v_pk_add_f32 v[68:69], v[68:69], v[182:183]
	v_cvt_pk_bf16_f32 v70, v70, v71
	v_cvt_pk_bf16_f32 v71, v72, v73
	v_cvt_pk_bf16_f32 v72, v66, v67
	v_cvt_pk_bf16_f32 v73, v68, v69
	global_store_dwordx4 v151, v[70:73], s[74:75] offset:256
	v_lshlrev_b32_e32 v212, 16, v70
	v_lshlrev_b32_e32 v213, 16, v71
	v_lshlrev_b32_e32 v214, 16, v72
	v_lshlrev_b32_e32 v215, 16, v73
	v_and_b32_e32 v66, 0xffff0000, v70
	v_and_b32_e32 v67, 0xffff0000, v71
	v_and_b32_e32 v68, 0xffff0000, v72
	v_and_b32_e32 v69, 0xffff0000, v73
	v_mul_f32_e32 v66, v66, v66
	v_mul_f32_e32 v67, v67, v67
	v_mul_f32_e32 v68, v68, v68
	v_mul_f32_e32 v69, v69, v69
	v_fmac_f32_e32 v66, v212, v212
	v_fmac_f32_e32 v67, v213, v213
	v_fmac_f32_e32 v68, v214, v214
	v_fmac_f32_e32 v69, v215, v215
	v_add_f32_e32 v66, v66, v67
	v_add_f32_e32 v66, v66, v68
	v_add_f32_e32 v66, v66, v69
	v_add_f32_e32 v74, v74, v66
	v_add_u32_e32 v151, 0x28000, v151
	s_waitcnt vmcnt(15)
	v_lshlrev_b32_e32 v182, 16, v216
	v_and_b32_e32 v183, 0xffff0000, v216
	v_pk_add_f32 v[60:61], v[60:61], v[182:183]
	v_lshlrev_b32_e32 v248, 16, v217
	v_and_b32_e32 v249, 0xffff0000, v217
	v_pk_add_f32 v[62:63], v[62:63], v[248:249]
	v_lshlrev_b32_e32 v138, 16, v218
	v_and_b32_e32 v139, 0xffff0000, v218
	v_pk_add_f32 v[56:57], v[56:57], v[138:139]
	v_lshlrev_b32_e32 v182, 16, v219
	v_and_b32_e32 v183, 0xffff0000, v219
	v_pk_add_f32 v[58:59], v[58:59], v[182:183]
	v_cvt_pk_bf16_f32 v60, v60, v61
	v_cvt_pk_bf16_f32 v61, v62, v63
	v_cvt_pk_bf16_f32 v62, v56, v57
	v_cvt_pk_bf16_f32 v63, v58, v59
	global_store_dwordx4 v151, v[60:63], s[74:75]
	v_lshlrev_b32_e32 v216, 16, v60
	v_lshlrev_b32_e32 v217, 16, v61
	v_lshlrev_b32_e32 v218, 16, v62
	v_lshlrev_b32_e32 v219, 16, v63
	v_and_b32_e32 v56, 0xffff0000, v60
	v_and_b32_e32 v57, 0xffff0000, v61
	v_and_b32_e32 v58, 0xffff0000, v62
	v_and_b32_e32 v59, 0xffff0000, v63
	v_mul_f32_e32 v56, v56, v56
	v_mul_f32_e32 v57, v57, v57
	v_mul_f32_e32 v58, v58, v58
	v_mul_f32_e32 v59, v59, v59
	v_fmac_f32_e32 v56, v216, v216
	v_fmac_f32_e32 v57, v217, v217
	v_fmac_f32_e32 v58, v218, v218
	v_fmac_f32_e32 v59, v219, v219
	v_add_f32_e32 v56, v56, v57
	v_add_f32_e32 v56, v56, v58
	v_add_f32_e32 v56, v56, v59
	s_waitcnt vmcnt(15)
	v_lshlrev_b32_e32 v182, 16, v220
	v_and_b32_e32 v183, 0xffff0000, v220
	v_pk_add_f32 v[52:53], v[52:53], v[182:183]
	v_lshlrev_b32_e32 v248, 16, v221
	v_and_b32_e32 v249, 0xffff0000, v221
	v_pk_add_f32 v[54:55], v[54:55], v[248:249]
	v_lshlrev_b32_e32 v138, 16, v222
	v_and_b32_e32 v139, 0xffff0000, v222
	v_pk_add_f32 v[48:49], v[48:49], v[138:139]
	v_lshlrev_b32_e32 v182, 16, v223
	v_and_b32_e32 v183, 0xffff0000, v223
	v_pk_add_f32 v[50:51], v[50:51], v[182:183]
	v_cvt_pk_bf16_f32 v52, v52, v53
	v_cvt_pk_bf16_f32 v53, v54, v55
	v_cvt_pk_bf16_f32 v54, v48, v49
	v_cvt_pk_bf16_f32 v55, v50, v51
	global_store_dwordx4 v151, v[52:55], s[74:75] offset:256
	v_lshlrev_b32_e32 v220, 16, v52
	v_lshlrev_b32_e32 v221, 16, v53
	v_lshlrev_b32_e32 v222, 16, v54
	v_lshlrev_b32_e32 v223, 16, v55
	v_and_b32_e32 v48, 0xffff0000, v52
	v_and_b32_e32 v49, 0xffff0000, v53
	v_and_b32_e32 v50, 0xffff0000, v54
	v_and_b32_e32 v51, 0xffff0000, v55
	v_mul_f32_e32 v48, v48, v48
	v_mul_f32_e32 v49, v49, v49
	v_mul_f32_e32 v50, v50, v50
	v_mul_f32_e32 v51, v51, v51
	v_fmac_f32_e32 v48, v220, v220
	v_fmac_f32_e32 v49, v221, v221
	v_fmac_f32_e32 v50, v222, v222
	v_fmac_f32_e32 v51, v223, v223
	v_add_f32_e32 v48, v48, v49
	v_add_f32_e32 v48, v48, v50
	v_add_f32_e32 v48, v48, v51
	v_add_f32_e32 v56, v56, v48
	v_add_u32_e32 v151, 0x8000, v151
	s_waitcnt vmcnt(15)
	v_lshlrev_b32_e32 v182, 16, v224
	v_and_b32_e32 v183, 0xffff0000, v224
	v_pk_add_f32 v[44:45], v[44:45], v[182:183]
	v_lshlrev_b32_e32 v248, 16, v225
	v_and_b32_e32 v249, 0xffff0000, v225
	v_pk_add_f32 v[46:47], v[46:47], v[248:249]
	v_lshlrev_b32_e32 v138, 16, v226
	v_and_b32_e32 v139, 0xffff0000, v226
	v_pk_add_f32 v[40:41], v[40:41], v[138:139]
	v_lshlrev_b32_e32 v182, 16, v227
	v_and_b32_e32 v183, 0xffff0000, v227
	v_pk_add_f32 v[42:43], v[42:43], v[182:183]
	v_cvt_pk_bf16_f32 v44, v44, v45
	v_cvt_pk_bf16_f32 v45, v46, v47
	v_cvt_pk_bf16_f32 v46, v40, v41
	v_cvt_pk_bf16_f32 v47, v42, v43
	global_store_dwordx4 v151, v[44:47], s[74:75]
	v_lshlrev_b32_e32 v224, 16, v44
	v_lshlrev_b32_e32 v225, 16, v45
	v_lshlrev_b32_e32 v226, 16, v46
	v_lshlrev_b32_e32 v227, 16, v47
	v_and_b32_e32 v40, 0xffff0000, v44
	v_and_b32_e32 v41, 0xffff0000, v45
	v_and_b32_e32 v42, 0xffff0000, v46
	v_and_b32_e32 v43, 0xffff0000, v47
	v_mul_f32_e32 v40, v40, v40
	v_mul_f32_e32 v41, v41, v41
	v_mul_f32_e32 v42, v42, v42
	v_mul_f32_e32 v43, v43, v43
	v_fmac_f32_e32 v40, v224, v224
	v_fmac_f32_e32 v41, v225, v225
	v_fmac_f32_e32 v42, v226, v226
	v_fmac_f32_e32 v43, v227, v227
	v_add_f32_e32 v40, v40, v41
	v_add_f32_e32 v40, v40, v42
	v_add_f32_e32 v40, v40, v43
	s_waitcnt vmcnt(15)
	v_lshlrev_b32_e32 v182, 16, v228
	v_and_b32_e32 v183, 0xffff0000, v228
	v_pk_add_f32 v[36:37], v[36:37], v[182:183]
	v_lshlrev_b32_e32 v248, 16, v229
	v_and_b32_e32 v249, 0xffff0000, v229
	v_pk_add_f32 v[38:39], v[38:39], v[248:249]
	v_lshlrev_b32_e32 v138, 16, v230
	v_and_b32_e32 v139, 0xffff0000, v230
	v_pk_add_f32 v[32:33], v[32:33], v[138:139]
	v_lshlrev_b32_e32 v182, 16, v231
	v_and_b32_e32 v183, 0xffff0000, v231
	v_pk_add_f32 v[34:35], v[34:35], v[182:183]
	v_cvt_pk_bf16_f32 v36, v36, v37
	v_cvt_pk_bf16_f32 v37, v38, v39
	v_cvt_pk_bf16_f32 v38, v32, v33
	v_cvt_pk_bf16_f32 v39, v34, v35
	global_store_dwordx4 v151, v[36:39], s[74:75] offset:256
	v_lshlrev_b32_e32 v228, 16, v36
	v_lshlrev_b32_e32 v229, 16, v37
	v_lshlrev_b32_e32 v230, 16, v38
	v_lshlrev_b32_e32 v231, 16, v39
	v_and_b32_e32 v32, 0xffff0000, v36
	v_and_b32_e32 v33, 0xffff0000, v37
	v_and_b32_e32 v34, 0xffff0000, v38
	v_and_b32_e32 v35, 0xffff0000, v39
	v_mul_f32_e32 v32, v32, v32
	v_mul_f32_e32 v33, v33, v33
	v_mul_f32_e32 v34, v34, v34
	v_mul_f32_e32 v35, v35, v35
	v_fmac_f32_e32 v32, v228, v228
	v_fmac_f32_e32 v33, v229, v229
	v_fmac_f32_e32 v34, v230, v230
	v_fmac_f32_e32 v35, v231, v231
	v_add_f32_e32 v32, v32, v33
	v_add_f32_e32 v32, v32, v34
	v_add_f32_e32 v32, v32, v35
	v_add_f32_e32 v40, v40, v32
	v_add_u32_e32 v151, 0x8000, v151
	s_waitcnt vmcnt(15)
	v_lshlrev_b32_e32 v182, 16, v232
	v_and_b32_e32 v183, 0xffff0000, v232
	v_pk_add_f32 v[28:29], v[28:29], v[182:183]
	v_lshlrev_b32_e32 v248, 16, v233
	v_and_b32_e32 v249, 0xffff0000, v233
	v_pk_add_f32 v[30:31], v[30:31], v[248:249]
	v_lshlrev_b32_e32 v138, 16, v234
	v_and_b32_e32 v139, 0xffff0000, v234
	v_pk_add_f32 v[24:25], v[24:25], v[138:139]
	v_lshlrev_b32_e32 v182, 16, v235
	v_and_b32_e32 v183, 0xffff0000, v235
	v_pk_add_f32 v[26:27], v[26:27], v[182:183]
	v_cvt_pk_bf16_f32 v28, v28, v29
	v_cvt_pk_bf16_f32 v29, v30, v31
	v_cvt_pk_bf16_f32 v30, v24, v25
	v_cvt_pk_bf16_f32 v31, v26, v27
	global_store_dwordx4 v151, v[28:31], s[74:75]
	v_lshlrev_b32_e32 v232, 16, v28
	v_lshlrev_b32_e32 v233, 16, v29
	v_lshlrev_b32_e32 v234, 16, v30
	v_lshlrev_b32_e32 v235, 16, v31
	v_and_b32_e32 v24, 0xffff0000, v28
	v_and_b32_e32 v25, 0xffff0000, v29
	v_and_b32_e32 v26, 0xffff0000, v30
	v_and_b32_e32 v27, 0xffff0000, v31
	v_mul_f32_e32 v24, v24, v24
	v_mul_f32_e32 v25, v25, v25
	v_mul_f32_e32 v26, v26, v26
	v_mul_f32_e32 v27, v27, v27
	v_fmac_f32_e32 v24, v232, v232
	v_fmac_f32_e32 v25, v233, v233
	v_fmac_f32_e32 v26, v234, v234
	v_fmac_f32_e32 v27, v235, v235
	v_add_f32_e32 v24, v24, v25
	v_add_f32_e32 v24, v24, v26
	v_add_f32_e32 v24, v24, v27
	s_waitcnt vmcnt(15)
	v_lshlrev_b32_e32 v182, 16, v236
	v_and_b32_e32 v183, 0xffff0000, v236
	v_pk_add_f32 v[20:21], v[20:21], v[182:183]
	v_lshlrev_b32_e32 v248, 16, v237
	v_and_b32_e32 v249, 0xffff0000, v237
	v_pk_add_f32 v[22:23], v[22:23], v[248:249]
	v_lshlrev_b32_e32 v138, 16, v238
	v_and_b32_e32 v139, 0xffff0000, v238
	v_pk_add_f32 v[16:17], v[16:17], v[138:139]
	v_lshlrev_b32_e32 v182, 16, v239
	v_and_b32_e32 v183, 0xffff0000, v239
	v_pk_add_f32 v[18:19], v[18:19], v[182:183]
	v_cvt_pk_bf16_f32 v20, v20, v21
	v_cvt_pk_bf16_f32 v21, v22, v23
	v_cvt_pk_bf16_f32 v22, v16, v17
	v_cvt_pk_bf16_f32 v23, v18, v19
	global_store_dwordx4 v151, v[20:23], s[74:75] offset:256
	v_lshlrev_b32_e32 v236, 16, v20
	v_lshlrev_b32_e32 v237, 16, v21
	v_lshlrev_b32_e32 v238, 16, v22
	v_lshlrev_b32_e32 v239, 16, v23
	v_and_b32_e32 v16, 0xffff0000, v20
	v_and_b32_e32 v17, 0xffff0000, v21
	v_and_b32_e32 v18, 0xffff0000, v22
	v_and_b32_e32 v19, 0xffff0000, v23
	v_mul_f32_e32 v16, v16, v16
	v_mul_f32_e32 v17, v17, v17
	v_mul_f32_e32 v18, v18, v18
	v_mul_f32_e32 v19, v19, v19
	v_fmac_f32_e32 v16, v236, v236
	v_fmac_f32_e32 v17, v237, v237
	v_fmac_f32_e32 v18, v238, v238
	v_fmac_f32_e32 v19, v239, v239
	v_add_f32_e32 v16, v16, v17
	v_add_f32_e32 v16, v16, v18
	v_add_f32_e32 v16, v16, v19
	v_add_f32_e32 v24, v24, v16
	v_add_u32_e32 v151, 0x8000, v151
	s_waitcnt vmcnt(15)
	v_lshlrev_b32_e32 v182, 16, v240
	v_and_b32_e32 v183, 0xffff0000, v240
	v_pk_add_f32 v[12:13], v[12:13], v[182:183]
	v_lshlrev_b32_e32 v248, 16, v241
	v_and_b32_e32 v249, 0xffff0000, v241
	v_pk_add_f32 v[14:15], v[14:15], v[248:249]
	v_lshlrev_b32_e32 v138, 16, v242
	v_and_b32_e32 v139, 0xffff0000, v242
	v_pk_add_f32 v[8:9], v[8:9], v[138:139]
	v_lshlrev_b32_e32 v182, 16, v243
	v_and_b32_e32 v183, 0xffff0000, v243
	v_pk_add_f32 v[10:11], v[10:11], v[182:183]
	v_cvt_pk_bf16_f32 v12, v12, v13
	v_cvt_pk_bf16_f32 v13, v14, v15
	v_cvt_pk_bf16_f32 v14, v8, v9
	v_cvt_pk_bf16_f32 v15, v10, v11
	global_store_dwordx4 v151, v[12:15], s[74:75]
	v_lshlrev_b32_e32 v240, 16, v12
	v_lshlrev_b32_e32 v241, 16, v13
	v_lshlrev_b32_e32 v242, 16, v14
	v_lshlrev_b32_e32 v243, 16, v15
	v_and_b32_e32 v8, 0xffff0000, v12
	v_and_b32_e32 v9, 0xffff0000, v13
	v_and_b32_e32 v10, 0xffff0000, v14
	v_and_b32_e32 v11, 0xffff0000, v15
	v_mul_f32_e32 v8, v8, v8
	v_mul_f32_e32 v9, v9, v9
	v_mul_f32_e32 v10, v10, v10
	v_mul_f32_e32 v11, v11, v11
	v_fmac_f32_e32 v8, v240, v240
	v_fmac_f32_e32 v9, v241, v241
	v_fmac_f32_e32 v10, v242, v242
	v_fmac_f32_e32 v11, v243, v243
	v_add_f32_e32 v8, v8, v9
	v_add_f32_e32 v8, v8, v10
	v_add_f32_e32 v8, v8, v11
	s_waitcnt vmcnt(15)
	v_lshlrev_b32_e32 v182, 16, v244
	v_and_b32_e32 v183, 0xffff0000, v244
	v_pk_add_f32 v[4:5], v[4:5], v[182:183]
	v_lshlrev_b32_e32 v248, 16, v245
	v_and_b32_e32 v249, 0xffff0000, v245
	v_pk_add_f32 v[6:7], v[6:7], v[248:249]
	v_lshlrev_b32_e32 v138, 16, v246
	v_and_b32_e32 v139, 0xffff0000, v246
	v_pk_add_f32 v[0:1], v[0:1], v[138:139]
	v_lshlrev_b32_e32 v182, 16, v247
	v_and_b32_e32 v183, 0xffff0000, v247
	v_pk_add_f32 v[2:3], v[2:3], v[182:183]
	v_cvt_pk_bf16_f32 v4, v4, v5
	v_cvt_pk_bf16_f32 v5, v6, v7
	v_cvt_pk_bf16_f32 v6, v0, v1
	v_cvt_pk_bf16_f32 v7, v2, v3
	global_store_dwordx4 v151, v[4:7], s[74:75] offset:256
	v_lshlrev_b32_e32 v244, 16, v4
	v_lshlrev_b32_e32 v245, 16, v5
	v_lshlrev_b32_e32 v246, 16, v6
	v_lshlrev_b32_e32 v247, 16, v7
	v_and_b32_e32 v0, 0xffff0000, v4
	v_and_b32_e32 v1, 0xffff0000, v5
	v_and_b32_e32 v2, 0xffff0000, v6
	v_and_b32_e32 v3, 0xffff0000, v7
	v_mul_f32_e32 v0, v0, v0
	v_mul_f32_e32 v1, v1, v1
	v_mul_f32_e32 v2, v2, v2
	v_mul_f32_e32 v3, v3, v3
	v_fmac_f32_e32 v0, v244, v244
	v_fmac_f32_e32 v1, v245, v245
	v_fmac_f32_e32 v2, v246, v246
	v_fmac_f32_e32 v3, v247, v247
	v_add_f32_e32 v0, v0, v1
	v_add_f32_e32 v0, v0, v2
	v_add_f32_e32 v0, v0, v3
	v_add_f32_e32 v8, v8, v0
	v_mov_b32_e32 v175, v122
	s_nop 1
	v_permlane16_swap_b32_e32 v175, v122
	v_add_f32_e32 v122, v175, v122
	v_mov_b32_e32 v175, v106
	s_nop 1
	v_permlane16_swap_b32_e32 v175, v106
	v_add_f32_e32 v106, v175, v106
	v_mov_b32_e32 v175, v90
	s_nop 1
	v_permlane16_swap_b32_e32 v175, v90
	v_add_f32_e32 v90, v175, v90
	v_mov_b32_e32 v175, v74
	s_nop 1
	v_permlane16_swap_b32_e32 v175, v74
	v_add_f32_e32 v74, v175, v74
	v_mov_b32_e32 v175, v56
	s_nop 1
	v_permlane16_swap_b32_e32 v175, v56
	v_add_f32_e32 v56, v175, v56
	v_mov_b32_e32 v175, v40
	s_nop 1
	v_permlane16_swap_b32_e32 v175, v40
	v_add_f32_e32 v40, v175, v40
	v_mov_b32_e32 v175, v24
	s_nop 1
	v_permlane16_swap_b32_e32 v175, v24
	v_add_f32_e32 v24, v175, v24
	v_mov_b32_e32 v175, v8
	s_nop 1
	v_permlane16_swap_b32_e32 v175, v8
	v_add_f32_e32 v8, v175, v8
	v_mov_b32_e32 v175, v122
	s_nop 1
	v_permlane32_swap_b32_e32 v175, v122
	v_add_f32_e32 v122, v175, v122
	v_mov_b32_e32 v175, v106
	s_nop 1
	v_permlane32_swap_b32_e32 v175, v106
	v_add_f32_e32 v106, v175, v106
	v_mov_b32_e32 v175, v90
	s_nop 1
	v_permlane32_swap_b32_e32 v175, v90
	v_add_f32_e32 v90, v175, v90
	v_mov_b32_e32 v175, v74
	s_nop 1
	v_permlane32_swap_b32_e32 v175, v74
	v_add_f32_e32 v74, v175, v74
	v_mov_b32_e32 v175, v56
	s_nop 1
	v_permlane32_swap_b32_e32 v175, v56
	v_add_f32_e32 v56, v175, v56
	v_mov_b32_e32 v175, v40
	s_nop 1
	v_permlane32_swap_b32_e32 v175, v40
	v_add_f32_e32 v40, v175, v40
	v_mov_b32_e32 v175, v24
	s_nop 1
	v_permlane32_swap_b32_e32 v175, v24
	v_add_f32_e32 v24, v175, v24
	v_mov_b32_e32 v175, v8
	s_nop 1
	v_permlane32_swap_b32_e32 v175, v8
	v_add_f32_e32 v8, v175, v8
	s_add_u32 s70, s28, s56
	s_addc_u32 s71, s29, 0
	s_and_saveexec_b64 s[4:5], s[38:39]
	s_nop 1
	global_store_dword v149, v122, s[70:71]
	v_add_u32_e32 v149, 0x400, v149
	global_store_dword v149, v106, s[70:71]
	v_add_u32_e32 v149, 0x400, v149
	global_store_dword v149, v90, s[70:71]
	v_add_u32_e32 v149, 0x400, v149
	global_store_dword v149, v74, s[70:71]
	v_add_u32_e32 v149, 0x1400, v149
	global_store_dword v149, v56, s[70:71]
	v_add_u32_e32 v149, 0x400, v149
	global_store_dword v149, v40, s[70:71]
	v_add_u32_e32 v149, 0x400, v149
	global_store_dword v149, v24, s[70:71]
	v_add_u32_e32 v149, 0x400, v149
	global_store_dword v149, v8, s[70:71]
	s_or_b64 exec, exec, s[4:5]
	s_mov_b32 s56, s57
	s_mov_b32 s57, 0
	s_lshl_b32 s76, s24, 2
	v_readlane_b32 s74, v255, 32
	v_readlane_b32 s75, v255, 33
	s_movk_i32 s78, 0xf800
	v_readlane_b32 s70, v255, 26
	v_readlane_b32 s71, v255, 27
	s_branch .Lxo_done
	v_lshl_add_u32 v150, s29, 8, v172
	s_lshl_b32 s4, s28, 8
	v_ashrrev_i32_e32 v151, 31, v150
	s_ashr_i32 s5, s4, 31
	v_lshlrev_b64 v[138:139], 11, v[150:151]
	v_mov_b32_e32 v149, s5
	v_or_b32_e32 v148, s4, v142
	v_lshl_add_u64 v[138:139], s[30:31], 0, v[138:139]
	v_lshl_add_u64 v[138:139], v[148:149], 1, v[138:139]
	global_load_dwordx4 v[184:187], v[138:139], off
	s_lshl_b32 s56, s28, 2
	s_ashr_i32 s57, s56, 31
	s_waitcnt vmcnt(0)
	v_lshlrev_b32_e32 v182, 16, v184
	v_and_b32_e32 v183, 0xffff0000, v184
	v_lshlrev_b32_e32 v184, 16, v185
	v_and_b32_e32 v185, 0xffff0000, v185
	v_lshlrev_b32_e32 v188, 16, v186
	v_and_b32_e32 v189, 0xffff0000, v186
	v_lshlrev_b32_e32 v186, 16, v187
	v_and_b32_e32 v187, 0xffff0000, v187
	v_pk_add_f32 v[126:127], v[126:127], v[182:183]
	v_pk_add_f32 v[128:129], v[128:129], v[184:185]
	v_pk_add_f32 v[182:183], v[124:125], v[186:187]
	v_pk_add_f32 v[122:123], v[122:123], v[188:189]
	v_cvt_pk_bf16_f32 v124, v126, v127
	v_cvt_pk_bf16_f32 v125, v128, v129
	s_nop 0
	v_cvt_pk_bf16_f32 v126, v122, v123
	v_cvt_pk_bf16_f32 v127, v182, v183
	global_load_dwordx4 v[184:187], v[138:139], off offset:256
	v_lshlrev_b32_e32 v128, 16, v124
	global_store_dwordx4 v[138:139], v[124:127], off
	v_lshlrev_b32_e32 v129, 16, v125
	v_lshlrev_b32_e32 v175, 16, v126
	v_and_b32_e32 v124, 0xffff0000, v124
	v_and_b32_e32 v125, 0xffff0000, v125
	v_and_b32_e32 v126, 0xffff0000, v126
	v_mul_f32_e32 v124, v124, v124
	v_mul_f32_e32 v125, v125, v125
	v_lshlrev_b32_e32 v182, 16, v127
	v_and_b32_e32 v127, 0xffff0000, v127
	v_mul_f32_e32 v126, v126, v126
	v_fmac_f32_e32 v124, v128, v128
	v_fmac_f32_e32 v125, v129, v129
	v_mul_f32_e32 v127, v127, v127
	v_fmac_f32_e32 v126, v175, v175
	v_add_f32_e32 v124, v124, v125
	v_fmac_f32_e32 v127, v182, v182
	v_add_f32_e32 v124, v124, v126
	v_add_f32_e32 v175, v124, v127
	v_and_b32_e32 v123, 64, v178
	v_xor_b32_e32 v122, 16, v178
	v_add_u32_e32 v123, 64, v123
	v_cmp_lt_i32_e32 vcc, v122, v123
	s_waitcnt vmcnt(1)
	v_lshlrev_b32_e32 v124, 16, v184
	v_and_b32_e32 v125, 0xffff0000, v184
	v_lshlrev_b32_e32 v126, 16, v185
	v_and_b32_e32 v127, 0xffff0000, v185
	v_lshlrev_b32_e32 v128, 16, v186
	v_and_b32_e32 v129, 0xffff0000, v186
	v_lshlrev_b32_e32 v182, 16, v187
	v_and_b32_e32 v183, 0xffff0000, v187
	v_pk_add_f32 v[120:121], v[120:121], v[126:127]
	v_pk_add_f32 v[118:119], v[118:119], v[124:125]
	v_pk_add_f32 v[116:117], v[116:117], v[182:183]
	v_pk_add_f32 v[114:115], v[114:115], v[128:129]
	v_cvt_pk_bf16_f32 v118, v118, v119
	v_cvt_pk_bf16_f32 v119, v120, v121
	v_cndmask_b32_e32 v122, v178, v122, vcc
	v_cvt_pk_bf16_f32 v120, v114, v115
	v_cvt_pk_bf16_f32 v121, v116, v117
	v_and_b32_e32 v115, 0xffff0000, v118
	v_and_b32_e32 v117, 0xffff0000, v119
	v_lshlrev_b32_e32 v114, 16, v118
	v_lshlrev_b32_e32 v116, 16, v119
	v_and_b32_e32 v125, 0xffff0000, v120
	v_mul_f32_e32 v115, v115, v115
	v_mul_f32_e32 v117, v117, v117
	v_lshlrev_b32_e32 v124, 16, v120
	v_and_b32_e32 v127, 0xffff0000, v121
	v_mul_f32_e32 v125, v125, v125
	v_fmac_f32_e32 v115, v114, v114
	v_fmac_f32_e32 v117, v116, v116
	v_lshlrev_b32_e32 v126, 16, v121
	v_mul_f32_e32 v127, v127, v127
	v_fmac_f32_e32 v125, v124, v124
	v_add_f32_e32 v114, v115, v117
	v_fmac_f32_e32 v127, v126, v126
	v_add_f32_e32 v114, v114, v125
	v_add_f32_e32 v114, v114, v127
	v_lshlrev_b32_e32 v122, 2, v122
	v_add_f32_e32 v114, v175, v114
	ds_bpermute_b32 v115, v122, v114
	v_xor_b32_e32 v116, 32, v178
	v_cmp_lt_i32_e32 vcc, v116, v123
	global_store_dwordx4 v[138:139], v[118:121], off offset:256
	s_waitcnt lgkmcnt(0)
	v_add_f32_e32 v114, v114, v115
	v_cndmask_b32_e32 v116, v178, v116, vcc
	v_lshlrev_b32_e32 v116, 2, v116
	ds_bpermute_b32 v115, v116, v114
	s_and_saveexec_b64 s[4:5], s[38:39]
	v_readlane_b32 s74, v255, 32
	v_readlane_b32 s75, v255, 33
	s_movk_i32 s78, 0xf800
	s_cbranch_execz .LBB0_112
	v_readlane_b32 s28, v250, 26
	s_waitcnt lgkmcnt(0)
	v_add_f32_e32 v117, v114, v115
	v_lshlrev_b64 v[114:115], 6, v[150:151]
	v_readlane_b32 s29, v250, 27
	s_lshl_b32 s76, s24, 2
	s_nop 0
	v_lshl_add_u64 v[114:115], s[28:29], 0, v[114:115]
	v_lshl_add_u64 v[114:115], s[56:57], 2, v[114:115]
	v_lshl_add_u64 v[114:115], v[114:115], 0, s[76:77]
	global_store_dword v[114:115], v117, off

.Lxo_done:
	s_andn2_b64 vcc, exec, s[40:41]
	s_mov_b64 s[4:5], -1
	s_cbranch_vccnz .LBB0_99
	s_andn2_b64 vcc, exec, s[36:37]
	s_cbranch_vccnz .LBB0_98
	s_barrier
	s_branch .LBB0_98
